# in-proj GEMM epilogue: 24 serialized row-scale loads replaced by two lane-distributed loads + ds_bpermute (same as up-GEMM), on top of v060
# speedup vs baseline: 1.0157x; 1.0031x over previous
; __device__ __forceinline__ unsigned cvt_pk_bf16(float lo, float hi) { unsigned r; asm volatile("v_cvt_pk_bf16_f32 %0, %1, %2" : "=v"(r) : "v"(lo), "v"(hi)); return r; }
; __device__ __forceinline__ float bf_lo(unsigned w) { return __uint_as_float(w << 16); }
; __device__ __forceinline__ float bf_hi(unsigned w) { return __uint_as_float(w & 0xffff0000u); }
; __device__ __forceinline__ float sigmoid_f(float x) { return __builtin_amdgcn_rcpf(1.0f + __builtin_amdgcn_exp2f(-1.4426950408889634f * x)); }
; #define RS ((float*)(WSP() + WS_RS))
;     __device__ __forceinline__ void operator()(const f32x4 (&acc)[2][2][4][2], const Unit& u, int wr, int wc, int fr, int fq) const {
;         const int row0 = u.pm * BM + wr * 64 + fr; const int col0 = u.pn * BM + wc * 32 + 8 * fq;
;         const float sc = (MODE == 2 && u.pn == qtile) ? qscale : 1.f;
; #pragma unroll
;         for (int ai = 0; ai < 2; ++ai)
; #pragma unroll
;             for (int m = 0; m < 4; ++m) { const size_t off = (size_t)(row0 + ai * HALF + m * 16) * ldc + col0; const float rs = (MODE != 0) ? RS[row0 + ai * HALF + m * 16] : 1.f;
; #pragma unroll
;                 for (int bj = 0; bj < 2; ++bj) { f32x4 v0 = acc[ai][bj][m][0], v1 = acc[ai][bj][m][1];
;                     if (MODE != 0) { v0 = v0 * rs; v1 = v1 * rs; }
;                     if (MODE == 1) {
; #pragma unroll
;                         for (int e = 0; e < 4; ++e) { const float a = fmaxf(v0[e], 0.f), b = fmaxf(v1[e], 0.f); v0[e] = a * a; v1[e] = b * b; } }
;                     if (MODE == 2) { v0 = v0 * sc; v1 = v1 * sc; }
;                     if (MODE == 3) { const u32x4 pw = *(const u32x4*)(P + off + bj * HALF);
;                         v0[0] = bf_lo(pw.x) * sigmoid_f(v0[0]); v0[1] = bf_hi(pw.x) * sigmoid_f(v0[1]); v0[2] = bf_lo(pw.y) * sigmoid_f(v0[2]); v0[3] = bf_hi(pw.y) * sigmoid_f(v0[3]);
;                         v1[0] = bf_lo(pw.z) * sigmoid_f(v1[0]); v1[1] = bf_hi(pw.z) * sigmoid_f(v1[1]); v1[2] = bf_lo(pw.w) * sigmoid_f(v1[2]); v1[3] = bf_hi(pw.w) * sigmoid_f(v1[3]); }
;                     u32x4 w; w.x = cvt_pk_bf16(v0[0], v0[1]); w.y = cvt_pk_bf16(v0[2], v0[3]); w.z = cvt_pk_bf16(v1[0], v1[1]); w.w = cvt_pk_bf16(v1[2], v1[3]);
;                     *(u32x4*)(O + off + bj * HALF) = w; } }
.LBB0_189:
	v_mbcnt_lo_u32_b32 v232, -1, 0
	v_mbcnt_hi_u32_b32 v232, -1, v232
	v_and_b32_e32 v233, 0xffffffc0, v156
	v_or_b32_e32 v232, v232, v233
	v_lshl_add_u32 v232, s24, 8, v232
	v_ashrrev_i32_e32 v233, 31, v232
	v_lshl_add_u64 v[232:233], v[232:233], 2, s[12:13]
	global_load_dword v242, v[232:233], off
	global_load_dword v243, v[232:233], off offset:512
	v_and_b32_e32 v234, 15, v156
	v_lshlrev_b32_e32 v234, 2, v234
	v_add_u32_e32 v235, 64, v234
	v_add_u32_e32 v236, 0x80, v234
	v_add_u32_e32 v237, 0xc0, v234
	v_mov_b32_e32 v238, v234
	v_mov_b32_e32 v239, v235
	v_mov_b32_e32 v240, v236
	v_mov_b32_e32 v241, v237
	s_waitcnt vmcnt(0)
	ds_bpermute_b32 v234, v234, v242
	ds_bpermute_b32 v235, v235, v242
	ds_bpermute_b32 v236, v236, v242
	ds_bpermute_b32 v237, v237, v242
	ds_bpermute_b32 v238, v238, v243
	ds_bpermute_b32 v239, v239, v243
	ds_bpermute_b32 v240, v240, v243
	ds_bpermute_b32 v241, v241, v243
	s_waitcnt lgkmcnt(0)
	v_lshl_add_u32 v150, s24, 8, v156
	v_ashrrev_i32_e32 v151, 31, v150
	v_lshl_add_u64 v[142:143], v[150:151], 2, s[12:13]
	s_nop 1
	v_mov_b32_e32 v160, v234
	s_cmp_eq_u32 s25, 2
	s_cselect_b64 vcc, -1, 0
	v_mov_b32_e32 v140, 0x3e38aa3b
	v_cndmask_b32_e32 v140, 1.0, v140, vcc
	v_lshl_or_b32 v148, s25, 8, v158
	v_ashrrev_i32_e32 v149, 31, v148
	v_add_u32_e32 v151, 0x80, v150
	s_and_b32 s17, s25, -2
	s_cmp_lg_u32 s17, 2
	v_pk_mul_f32 v[144:145], v[126:127], v[160:161] op_sel_hi:[1,0]
	v_pk_mul_f32 v[146:147], v[128:129], v[160:161] op_sel_hi:[1,0]
	v_pk_mul_f32 v[152:153], v[122:123], v[160:161] op_sel_hi:[1,0]
	v_pk_mul_f32 v[154:155], v[124:125], v[160:161] op_sel_hi:[1,0]
	v_pk_mul_f32 v[146:147], v[140:141], v[146:147] op_sel_hi:[0,1]
	v_pk_mul_f32 v[144:145], v[140:141], v[144:145] op_sel_hi:[0,1]
	v_pk_mul_f32 v[152:153], v[140:141], v[152:153] op_sel_hi:[0,1]
	v_pk_mul_f32 v[154:155], v[140:141], v[154:155] op_sel_hi:[0,1]
	v_cvt_pk_bf16_f32 v144, v144, v145
	v_cvt_pk_bf16_f32 v145, v146, v147
	v_cvt_pk_bf16_f32 v146, v152, v153
	v_mov_b64_e32 v[152:153], s[10:11]
	v_cvt_pk_bf16_f32 v147, v154, v155
	v_mad_i64_i32 v[162:163], s[26:27], v150, s97, v[152:153]
	v_lshlrev_b64 v[154:155], 1, v[148:149]
	v_lshl_add_u64 v[148:149], v[162:163], 0, v[154:155]
	global_store_dwordx4 v[148:149], v[144:147], off
	v_pk_mul_f32 v[162:163], v[82:83], v[160:161] op_sel_hi:[1,0]
	s_nop 0
	v_pk_mul_f32 v[144:145], v[90:91], v[160:161] op_sel_hi:[1,0]
	v_pk_mul_f32 v[146:147], v[92:93], v[160:161] op_sel_hi:[1,0]
	v_pk_mul_f32 v[160:161], v[84:85], v[160:161] op_sel_hi:[1,0]
	v_pk_mul_f32 v[146:147], v[140:141], v[146:147] op_sel_hi:[0,1]
	v_pk_mul_f32 v[144:145], v[140:141], v[144:145] op_sel_hi:[0,1]
	v_pk_mul_f32 v[160:161], v[140:141], v[160:161] op_sel_hi:[0,1]
	v_pk_mul_f32 v[162:163], v[140:141], v[162:163] op_sel_hi:[0,1]
	v_cvt_pk_bf16_f32 v144, v144, v145
	v_cvt_pk_bf16_f32 v145, v146, v147
	v_cvt_pk_bf16_f32 v146, v162, v163
	v_cvt_pk_bf16_f32 v147, v160, v161
	v_or_b32_e32 v160, 16, v150
	v_ashrrev_i32_e32 v161, 31, v160
	global_store_dwordx4 v[148:149], v[144:147], off offset:256
	s_nop 1
	v_lshl_add_u64 v[144:145], v[160:161], 2, s[12:13]
	s_nop 1
	v_mov_b32_e32 v162, v235
	v_mad_i64_i32 v[160:161], s[26:27], v160, s97, v[152:153]
	v_lshl_add_u64 v[160:161], v[160:161], 0, v[154:155]
	v_pk_mul_f32 v[146:147], v[118:119], v[162:163] op_sel_hi:[1,0]
	v_pk_mul_f32 v[148:149], v[120:121], v[162:163] op_sel_hi:[1,0]
	v_pk_mul_f32 v[164:165], v[114:115], v[162:163] op_sel_hi:[1,0]
	v_pk_mul_f32 v[166:167], v[116:117], v[162:163] op_sel_hi:[1,0]
	v_pk_mul_f32 v[148:149], v[140:141], v[148:149] op_sel_hi:[0,1]
	v_pk_mul_f32 v[146:147], v[140:141], v[146:147] op_sel_hi:[0,1]
	v_pk_mul_f32 v[166:167], v[140:141], v[166:167] op_sel_hi:[0,1]
	v_pk_mul_f32 v[164:165], v[140:141], v[164:165] op_sel_hi:[0,1]
	v_cvt_pk_bf16_f32 v146, v146, v147
	v_cvt_pk_bf16_f32 v147, v148, v149
	v_cvt_pk_bf16_f32 v148, v164, v165
	v_cvt_pk_bf16_f32 v149, v166, v167
	global_store_dwordx4 v[160:161], v[146:149], off
	v_pk_mul_f32 v[164:165], v[74:75], v[162:163] op_sel_hi:[1,0]
	s_nop 0
	v_pk_mul_f32 v[146:147], v[78:79], v[162:163] op_sel_hi:[1,0]
	v_pk_mul_f32 v[148:149], v[80:81], v[162:163] op_sel_hi:[1,0]
	v_pk_mul_f32 v[146:147], v[140:141], v[146:147] op_sel_hi:[0,1]
	v_pk_mul_f32 v[148:149], v[140:141], v[148:149] op_sel_hi:[0,1]
	v_pk_mul_f32 v[162:163], v[76:77], v[162:163] op_sel_hi:[1,0]
	v_pk_mul_f32 v[164:165], v[140:141], v[164:165] op_sel_hi:[0,1]
	v_cvt_pk_bf16_f32 v146, v146, v147
	v_cvt_pk_bf16_f32 v147, v148, v149
	v_cvt_pk_bf16_f32 v148, v164, v165
	v_pk_mul_f32 v[162:163], v[140:141], v[162:163] op_sel_hi:[0,1]
	v_cvt_pk_bf16_f32 v149, v162, v163
	global_store_dwordx4 v[160:161], v[146:149], off offset:256
	s_nop 1
	v_or_b32_e32 v148, 32, v150
	v_ashrrev_i32_e32 v149, 31, v148
	v_lshl_add_u64 v[146:147], v[148:149], 2, s[12:13]
	s_nop 1
	v_mov_b32_e32 v164, v236
	v_mad_i64_i32 v[148:149], s[26:27], v148, s97, v[152:153]
	v_lshl_add_u64 v[148:149], v[148:149], 0, v[154:155]
	v_pk_mul_f32 v[160:161], v[110:111], v[164:165] op_sel_hi:[1,0]
	v_pk_mul_f32 v[162:163], v[112:113], v[164:165] op_sel_hi:[1,0]
	v_pk_mul_f32 v[166:167], v[106:107], v[164:165] op_sel_hi:[1,0]
	v_pk_mul_f32 v[168:169], v[108:109], v[164:165] op_sel_hi:[1,0]
	v_pk_mul_f32 v[162:163], v[140:141], v[162:163] op_sel_hi:[0,1]
	v_pk_mul_f32 v[160:161], v[140:141], v[160:161] op_sel_hi:[0,1]
	v_pk_mul_f32 v[168:169], v[140:141], v[168:169] op_sel_hi:[0,1]
	v_pk_mul_f32 v[166:167], v[140:141], v[166:167] op_sel_hi:[0,1]
	v_cvt_pk_bf16_f32 v160, v160, v161
	v_cvt_pk_bf16_f32 v161, v162, v163
	v_cvt_pk_bf16_f32 v162, v166, v167
	v_cvt_pk_bf16_f32 v163, v168, v169
; __device__ __forceinline__ unsigned cvt_pk_bf16(float lo, float hi) { unsigned r; asm volatile("v_cvt_pk_bf16_f32 %0, %1, %2" : "=v"(r) : "v"(lo), "v"(hi)); return r; }
; __device__ __forceinline__ float bf_lo(unsigned w) { return __uint_as_float(w << 16); }
; __device__ __forceinline__ float bf_hi(unsigned w) { return __uint_as_float(w & 0xffff0000u); }
; __device__ __forceinline__ float sigmoid_f(float x) { return __builtin_amdgcn_rcpf(1.0f + __builtin_amdgcn_exp2f(-1.4426950408889634f * x)); }
; #define RS ((float*)(WSP() + WS_RS))
;     __device__ __forceinline__ void operator()(const f32x4 (&acc)[2][2][4][2], const Unit& u, int wr, int wc, int fr, int fq) const {
;     ...
;             for (int m = 0; m < 4; ++m) { const size_t off = (size_t)(row0 + ai * HALF + m * 16) * ldc + col0; const float rs = (MODE != 0) ? RS[row0 + ai * HALF + m * 16] : 1.f;
; #pragma unroll
;                 for (int bj = 0; bj < 2; ++bj) { f32x4 v0 = acc[ai][bj][m][0], v1 = acc[ai][bj][m][1];
;                     if (MODE != 0) { v0 = v0 * rs; v1 = v1 * rs; }
;                     if (MODE == 1) {
; #pragma unroll
;                         for (int e = 0; e < 4; ++e) { const float a = fmaxf(v0[e], 0.f), b = fmaxf(v1[e], 0.f); v0[e] = a * a; v1[e] = b * b; } }
;                     if (MODE == 2) { v0 = v0 * sc; v1 = v1 * sc; }
;                     if (MODE == 3) { const u32x4 pw = *(const u32x4*)(P + off + bj * HALF);
;                         v0[0] = bf_lo(pw.x) * sigmoid_f(v0[0]); v0[1] = bf_hi(pw.x) * sigmoid_f(v0[1]); v0[2] = bf_lo(pw.y) * sigmoid_f(v0[2]); v0[3] = bf_hi(pw.y) * sigmoid_f(v0[3]);
;                         v1[0] = bf_lo(pw.z) * sigmoid_f(v1[0]); v1[1] = bf_hi(pw.z) * sigmoid_f(v1[1]); v1[2] = bf_lo(pw.w) * sigmoid_f(v1[2]); v1[3] = bf_hi(pw.w) * sigmoid_f(v1[3]); }
;                     u32x4 w; w.x = cvt_pk_bf16(v0[0], v0[1]); w.y = cvt_pk_bf16(v0[2], v0[3]); w.z = cvt_pk_bf16(v1[0], v1[1]); w.w = cvt_pk_bf16(v1[2], v1[3]);
;                     *(u32x4*)(O + off + bj * HALF) = w; } }
	global_store_dwordx4 v[148:149], v[160:163], off
	v_pk_mul_f32 v[166:167], v[86:87], v[164:165] op_sel_hi:[1,0]
	s_nop 0
	v_pk_mul_f32 v[160:161], v[94:95], v[164:165] op_sel_hi:[1,0]
	v_pk_mul_f32 v[162:163], v[96:97], v[164:165] op_sel_hi:[1,0]
	v_pk_mul_f32 v[164:165], v[88:89], v[164:165] op_sel_hi:[1,0]
	v_pk_mul_f32 v[162:163], v[140:141], v[162:163] op_sel_hi:[0,1]
	v_pk_mul_f32 v[160:161], v[140:141], v[160:161] op_sel_hi:[0,1]
	v_pk_mul_f32 v[164:165], v[140:141], v[164:165] op_sel_hi:[0,1]
	v_pk_mul_f32 v[166:167], v[140:141], v[166:167] op_sel_hi:[0,1]
	v_cvt_pk_bf16_f32 v160, v160, v161
	v_cvt_pk_bf16_f32 v161, v162, v163
	v_cvt_pk_bf16_f32 v162, v166, v167
	v_cvt_pk_bf16_f32 v163, v164, v165
	v_or_b32_e32 v164, 48, v150
	v_ashrrev_i32_e32 v165, 31, v164
	global_store_dwordx4 v[148:149], v[160:163], off offset:256
	v_lshl_add_u64 v[148:149], v[164:165], 2, s[12:13]
	s_nop 1
	v_mov_b32_e32 v166, v237
	v_mad_i64_i32 v[164:165], s[26:27], v164, s97, v[152:153]
	v_lshl_add_u64 v[164:165], v[164:165], 0, v[154:155]
	v_pk_mul_f32 v[160:161], v[102:103], v[166:167] op_sel_hi:[1,0]
	v_pk_mul_f32 v[162:163], v[104:105], v[166:167] op_sel_hi:[1,0]
	v_pk_mul_f32 v[168:169], v[98:99], v[166:167] op_sel_hi:[1,0]
	v_pk_mul_f32 v[170:171], v[100:101], v[166:167] op_sel_hi:[1,0]
	v_pk_mul_f32 v[162:163], v[140:141], v[162:163] op_sel_hi:[0,1]
	v_pk_mul_f32 v[160:161], v[140:141], v[160:161] op_sel_hi:[0,1]
	v_pk_mul_f32 v[170:171], v[140:141], v[170:171] op_sel_hi:[0,1]
	v_pk_mul_f32 v[168:169], v[140:141], v[168:169] op_sel_hi:[0,1]
	v_cvt_pk_bf16_f32 v160, v160, v161
	v_cvt_pk_bf16_f32 v161, v162, v163
	v_cvt_pk_bf16_f32 v162, v168, v169
	v_cvt_pk_bf16_f32 v163, v170, v171
	global_store_dwordx4 v[164:165], v[160:163], off
	v_pk_mul_f32 v[168:169], v[66:67], v[166:167] op_sel_hi:[1,0]
	s_nop 0
	v_pk_mul_f32 v[160:161], v[70:71], v[166:167] op_sel_hi:[1,0]
	v_pk_mul_f32 v[162:163], v[72:73], v[166:167] op_sel_hi:[1,0]
	v_pk_mul_f32 v[166:167], v[68:69], v[166:167] op_sel_hi:[1,0]
	v_pk_mul_f32 v[162:163], v[140:141], v[162:163] op_sel_hi:[0,1]
	v_pk_mul_f32 v[160:161], v[140:141], v[160:161] op_sel_hi:[0,1]
	v_pk_mul_f32 v[166:167], v[140:141], v[166:167] op_sel_hi:[0,1]
	v_pk_mul_f32 v[168:169], v[140:141], v[168:169] op_sel_hi:[0,1]
	v_cvt_pk_bf16_f32 v160, v160, v161
	v_cvt_pk_bf16_f32 v161, v162, v163
	v_cvt_pk_bf16_f32 v162, v168, v169
	v_cvt_pk_bf16_f32 v163, v166, v167
	global_store_dwordx4 v[164:165], v[160:163], off offset:256
	s_nop 1
	v_mov_b32_e32 v164, v238
	v_pk_mul_f32 v[166:167], v[58:59], v[164:165] op_sel_hi:[1,0]
	v_pk_mul_f32 v[160:161], v[62:63], v[164:165] op_sel_hi:[1,0]
	v_pk_mul_f32 v[162:163], v[64:65], v[164:165] op_sel_hi:[1,0]
	v_pk_mul_f32 v[160:161], v[140:141], v[160:161] op_sel_hi:[0,1]
	v_pk_mul_f32 v[162:163], v[140:141], v[162:163] op_sel_hi:[0,1]
	v_pk_mul_f32 v[166:167], v[140:141], v[166:167] op_sel_hi:[0,1]
	v_pk_mul_f32 v[168:169], v[60:61], v[164:165] op_sel_hi:[1,0]
	v_cvt_pk_bf16_f32 v160, v160, v161
	v_cvt_pk_bf16_f32 v161, v162, v163
	v_cvt_pk_bf16_f32 v162, v166, v167
	v_mad_i64_i32 v[166:167], s[26:27], v151, s97, v[152:153]
	v_pk_mul_f32 v[168:169], v[140:141], v[168:169] op_sel_hi:[0,1]
	v_cvt_pk_bf16_f32 v163, v168, v169
	v_lshl_add_u64 v[166:167], v[166:167], 0, v[154:155]
	global_store_dwordx4 v[166:167], v[160:163], off
	v_pk_mul_f32 v[168:169], v[18:19], v[164:165] op_sel_hi:[1,0]
	v_add_u32_e32 v151, 0x90, v150
	v_pk_mul_f32 v[160:161], v[26:27], v[164:165] op_sel_hi:[1,0]
	v_pk_mul_f32 v[162:163], v[28:29], v[164:165] op_sel_hi:[1,0]
	v_pk_mul_f32 v[164:165], v[20:21], v[164:165] op_sel_hi:[1,0]
	v_pk_mul_f32 v[162:163], v[140:141], v[162:163] op_sel_hi:[0,1]
	v_pk_mul_f32 v[160:161], v[140:141], v[160:161] op_sel_hi:[0,1]
	v_pk_mul_f32 v[164:165], v[140:141], v[164:165] op_sel_hi:[0,1]
	v_pk_mul_f32 v[168:169], v[140:141], v[168:169] op_sel_hi:[0,1]
	v_cvt_pk_bf16_f32 v160, v160, v161
	v_cvt_pk_bf16_f32 v161, v162, v163
	v_cvt_pk_bf16_f32 v162, v168, v169
	v_cvt_pk_bf16_f32 v163, v164, v165
	global_store_dwordx4 v[166:167], v[160:163], off offset:256
	s_nop 1
	v_mov_b32_e32 v164, v239
	v_pk_mul_f32 v[166:167], v[50:51], v[164:165] op_sel_hi:[1,0]
	v_pk_mul_f32 v[160:161], v[54:55], v[164:165] op_sel_hi:[1,0]
	v_pk_mul_f32 v[162:163], v[56:57], v[164:165] op_sel_hi:[1,0]
	v_pk_mul_f32 v[160:161], v[140:141], v[160:161] op_sel_hi:[0,1]
	v_pk_mul_f32 v[162:163], v[140:141], v[162:163] op_sel_hi:[0,1]
	v_pk_mul_f32 v[166:167], v[140:141], v[166:167] op_sel_hi:[0,1]
	v_pk_mul_f32 v[168:169], v[52:53], v[164:165] op_sel_hi:[1,0]
	v_cvt_pk_bf16_f32 v160, v160, v161
	v_cvt_pk_bf16_f32 v161, v162, v163
	v_cvt_pk_bf16_f32 v162, v166, v167
	v_mad_i64_i32 v[166:167], s[26:27], v151, s97, v[152:153]
	v_pk_mul_f32 v[168:169], v[140:141], v[168:169] op_sel_hi:[0,1]
	v_cvt_pk_bf16_f32 v163, v168, v169
	v_lshl_add_u64 v[166:167], v[166:167], 0, v[154:155]
	global_store_dwordx4 v[166:167], v[160:163], off
	v_pk_mul_f32 v[168:169], v[10:11], v[164:165] op_sel_hi:[1,0]
	v_add_u32_e32 v151, 0xa0, v150
	v_pk_mul_f32 v[160:161], v[14:15], v[164:165] op_sel_hi:[1,0]
	v_pk_mul_f32 v[162:163], v[16:17], v[164:165] op_sel_hi:[1,0]
	v_pk_mul_f32 v[164:165], v[12:13], v[164:165] op_sel_hi:[1,0]
	v_pk_mul_f32 v[162:163], v[140:141], v[162:163] op_sel_hi:[0,1]
	v_pk_mul_f32 v[160:161], v[140:141], v[160:161] op_sel_hi:[0,1]
	v_pk_mul_f32 v[164:165], v[140:141], v[164:165] op_sel_hi:[0,1]
	v_pk_mul_f32 v[168:169], v[140:141], v[168:169] op_sel_hi:[0,1]
	v_cvt_pk_bf16_f32 v160, v160, v161
	v_cvt_pk_bf16_f32 v161, v162, v163
	v_cvt_pk_bf16_f32 v162, v168, v169
	v_cvt_pk_bf16_f32 v163, v164, v165
; __device__ __forceinline__ unsigned cvt_pk_bf16(float lo, float hi) { unsigned r; asm volatile("v_cvt_pk_bf16_f32 %0, %1, %2" : "=v"(r) : "v"(lo), "v"(hi)); return r; }
; #define RS ((float*)(WSP() + WS_RS))
;     __device__ __forceinline__ void operator()(const f32x4 (&acc)[2][2][4][2], const Unit& u, int wr, int wc, int fr, int fq) const {
;     ...
;             for (int m = 0; m < 4; ++m) { const size_t off = (size_t)(row0 + ai * HALF + m * 16) * ldc + col0; const float rs = (MODE != 0) ? RS[row0 + ai * HALF + m * 16] : 1.f;
; #pragma unroll
;                 for (int bj = 0; bj < 2; ++bj) { f32x4 v0 = acc[ai][bj][m][0], v1 = acc[ai][bj][m][1];
;                     if (MODE != 0) { v0 = v0 * rs; v1 = v1 * rs; }
;                     if (MODE == 1) {
; #pragma unroll
;                         for (int e = 0; e < 4; ++e) { const float a = fmaxf(v0[e], 0.f), b = fmaxf(v1[e], 0.f); v0[e] = a * a; v1[e] = b * b; } }
;                     if (MODE == 2) { v0 = v0 * sc; v1 = v1 * sc; }
;                     if (MODE == 3) { const u32x4 pw = *(const u32x4*)(P + off + bj * HALF);
;                         v0[0] = bf_lo(pw.x) * sigmoid_f(v0[0]); v0[1] = bf_hi(pw.x) * sigmoid_f(v0[1]); v0[2] = bf_lo(pw.y) * sigmoid_f(v0[2]); v0[3] = bf_hi(pw.y) * sigmoid_f(v0[3]);
;                         v1[0] = bf_lo(pw.z) * sigmoid_f(v1[0]); v1[1] = bf_hi(pw.z) * sigmoid_f(v1[1]); v1[2] = bf_lo(pw.w) * sigmoid_f(v1[2]); v1[3] = bf_hi(pw.w) * sigmoid_f(v1[3]); }
;                     u32x4 w; w.x = cvt_pk_bf16(v0[0], v0[1]); w.y = cvt_pk_bf16(v0[2], v0[3]); w.z = cvt_pk_bf16(v1[0], v1[1]); w.w = cvt_pk_bf16(v1[2], v1[3]);
;                     *(u32x4*)(O + off + bj * HALF) = w; } }
;         if (MODE == 2) { if (u.pn == qtile || u.pn == qtile + 1) {
; #pragma unroll
;             for (int ai = 0; ai < 2; ++ai)
; #pragma unroll
;                 for (int bj = 0; bj < 2; ++bj) { float mx = 0.f;
; #pragma unroll
;                     for (int m = 0; m < 4; ++m) { const float rs = RS[row0 + ai * HALF + m * 16] * sc; const f32x4 v0 = acc[ai][bj][m][0] * rs, v1 = acc[ai][bj][m][1] * rs;
;                         float ss = ((v0[0] * v0[0] + v0[1] * v0[1]) + (v0[2] * v0[2] + v0[3] * v0[3])) + ((v1[0] * v1[0] + v1[1] * v1[1]) + (v1[2] * v1[2] + v1[3] * v1[3]));
;                         ss += __shfl_xor(ss, 16); ss += __shfl_xor(ss, 32); mx = fmaxf(mx, ss); }
	global_store_dwordx4 v[166:167], v[160:163], off offset:256
	s_nop 1
	v_mov_b32_e32 v164, v240
	v_pk_mul_f32 v[166:167], v[42:43], v[164:165] op_sel_hi:[1,0]
	v_pk_mul_f32 v[160:161], v[46:47], v[164:165] op_sel_hi:[1,0]
	v_pk_mul_f32 v[162:163], v[48:49], v[164:165] op_sel_hi:[1,0]
	v_pk_mul_f32 v[160:161], v[140:141], v[160:161] op_sel_hi:[0,1]
	v_pk_mul_f32 v[162:163], v[140:141], v[162:163] op_sel_hi:[0,1]
	v_pk_mul_f32 v[166:167], v[140:141], v[166:167] op_sel_hi:[0,1]
	v_pk_mul_f32 v[168:169], v[44:45], v[164:165] op_sel_hi:[1,0]
	v_cvt_pk_bf16_f32 v160, v160, v161
	v_cvt_pk_bf16_f32 v161, v162, v163
	v_cvt_pk_bf16_f32 v162, v166, v167
	v_mad_i64_i32 v[166:167], s[26:27], v151, s97, v[152:153]
	v_pk_mul_f32 v[168:169], v[140:141], v[168:169] op_sel_hi:[0,1]
	v_cvt_pk_bf16_f32 v163, v168, v169
	v_lshl_add_u64 v[166:167], v[166:167], 0, v[154:155]
	global_store_dwordx4 v[166:167], v[160:163], off
	v_pk_mul_f32 v[168:169], v[22:23], v[164:165] op_sel_hi:[1,0]
	v_add_u32_e32 v151, 0xb0, v150
	v_pk_mul_f32 v[160:161], v[30:31], v[164:165] op_sel_hi:[1,0]
	v_pk_mul_f32 v[162:163], v[32:33], v[164:165] op_sel_hi:[1,0]
	v_pk_mul_f32 v[164:165], v[24:25], v[164:165] op_sel_hi:[1,0]
	v_pk_mul_f32 v[162:163], v[140:141], v[162:163] op_sel_hi:[0,1]
	v_pk_mul_f32 v[160:161], v[140:141], v[160:161] op_sel_hi:[0,1]
	v_pk_mul_f32 v[164:165], v[140:141], v[164:165] op_sel_hi:[0,1]
	v_pk_mul_f32 v[168:169], v[140:141], v[168:169] op_sel_hi:[0,1]
	v_cvt_pk_bf16_f32 v160, v160, v161
	v_cvt_pk_bf16_f32 v161, v162, v163
	v_cvt_pk_bf16_f32 v162, v168, v169
	v_cvt_pk_bf16_f32 v163, v164, v165
	global_store_dwordx4 v[166:167], v[160:163], off offset:256
	s_nop 1
	v_mov_b32_e32 v150, v241
	v_mad_i64_i32 v[152:153], s[26:27], v151, s97, v[152:153]
	v_lshl_add_u64 v[154:155], v[152:153], 0, v[154:155]
	v_pk_mul_f32 v[160:161], v[38:39], v[150:151] op_sel_hi:[1,0]
	v_pk_mul_f32 v[162:163], v[40:41], v[150:151] op_sel_hi:[1,0]
	v_pk_mul_f32 v[164:165], v[34:35], v[150:151] op_sel_hi:[1,0]
	v_pk_mul_f32 v[166:167], v[36:37], v[150:151] op_sel_hi:[1,0]
	v_pk_mul_f32 v[162:163], v[140:141], v[162:163] op_sel_hi:[0,1]
	v_pk_mul_f32 v[160:161], v[140:141], v[160:161] op_sel_hi:[0,1]
	v_pk_mul_f32 v[166:167], v[140:141], v[166:167] op_sel_hi:[0,1]
	v_pk_mul_f32 v[164:165], v[140:141], v[164:165] op_sel_hi:[0,1]
	v_cvt_pk_bf16_f32 v160, v160, v161
	v_cvt_pk_bf16_f32 v161, v162, v163
	v_cvt_pk_bf16_f32 v162, v164, v165
	v_cvt_pk_bf16_f32 v163, v166, v167
	v_pk_mul_f32 v[152:153], v[6:7], v[150:151] op_sel_hi:[1,0]
	global_store_dwordx4 v[154:155], v[160:163], off
	v_pk_mul_f32 v[152:153], v[140:141], v[152:153] op_sel_hi:[0,1]
	s_nop 0
	v_pk_mul_f32 v[160:161], v[8:9], v[150:151] op_sel_hi:[1,0]
	v_pk_mul_f32 v[162:163], v[2:3], v[150:151] op_sel_hi:[1,0]
	v_pk_mul_f32 v[150:151], v[4:5], v[150:151] op_sel_hi:[1,0]
	v_pk_mul_f32 v[160:161], v[140:141], v[160:161] op_sel_hi:[0,1]
	v_pk_mul_f32 v[164:165], v[140:141], v[150:151] op_sel_hi:[0,1]
	v_pk_mul_f32 v[162:163], v[140:141], v[162:163] op_sel_hi:[0,1]
	v_cvt_pk_bf16_f32 v150, v152, v153
	v_cvt_pk_bf16_f32 v151, v160, v161
	v_cvt_pk_bf16_f32 v152, v162, v163
	v_cvt_pk_bf16_f32 v153, v164, v165
	global_store_dwordx4 v[154:155], v[150:153], off offset:256
	s_cbranch_scc1 .LBB0_199
	s_nop 1
	v_mov_b32_e32 v160, v234
	v_cmp_lt_i32_e32 vcc, v208, v203
	s_lshl_b32 s19, s25, 12
	s_lshl_b32 s17, s24, 4
	v_cndmask_b32_e32 v150, v201, v208, vcc
	v_lshlrev_b32_e32 v155, 2, v150
	v_cmp_lt_i32_e32 vcc, v209, v203
	s_add_i32 s19, s81, s19
	s_add_i32 s17, s19, s17
	v_cndmask_b32_e32 v150, v201, v209, vcc
	v_lshlrev_b32_e32 v154, 2, v150
	v_cmp_lt_i32_e32 vcc, v204, v203
	s_or_b32 s24, s17, s78
	v_mul_f32_e32 v160, v140, v160
	v_pk_mul_f32 v[126:127], v[126:127], v[160:161] op_sel_hi:[1,0]
	v_pk_mul_f32 v[122:123], v[122:123], v[160:161] op_sel_hi:[1,0]
	v_pk_mul_f32 v[128:129], v[128:129], v[160:161] op_sel_hi:[1,0]
	v_pk_mul_f32 v[124:125], v[124:125], v[160:161] op_sel_hi:[1,0]
	v_mul_f32_e32 v127, v127, v127
	v_mul_f32_e32 v123, v123, v123
	v_fmac_f32_e32 v127, v126, v126
	v_mul_f32_e32 v126, v129, v129
	v_fmac_f32_e32 v123, v122, v122
	v_mul_f32_e32 v122, v125, v125
	v_fmac_f32_e32 v126, v128, v128
	v_fmac_f32_e32 v122, v124, v124
	v_add_f32_e32 v126, v127, v126
	v_add_f32_e32 v122, v123, v122
	v_add_f32_e32 v122, v126, v122
	ds_bpermute_b32 v123, v155, v122
	v_cndmask_b32_e32 v150, v201, v204, vcc
	v_lshlrev_b32_e32 v150, 2, v150
	v_cmp_lt_i32_e32 vcc, v205, v203
	s_waitcnt lgkmcnt(0)
	v_add_f32_e32 v122, v122, v123
	ds_bpermute_b32 v123, v154, v122
	v_cndmask_b32_e32 v151, v201, v205, vcc
	v_lshlrev_b32_e32 v151, 2, v151
	v_cmp_lt_i32_e32 vcc, v206, v203
	s_waitcnt lgkmcnt(0)
	v_add_f32_e32 v123, v122, v123
	s_nop 1
	v_mov_b32_e32 v122, v235
	v_cndmask_b32_e32 v152, v201, v206, vcc
	v_lshlrev_b32_e32 v152, 2, v152
	v_cmp_lt_i32_e32 vcc, v207, v203
	v_mul_f32_e32 v122, v140, v122
	v_pk_mul_f32 v[118:119], v[118:119], v[122:123] op_sel_hi:[1,0]
	v_pk_mul_f32 v[114:115], v[114:115], v[122:123] op_sel_hi:[1,0]
	v_pk_mul_f32 v[120:121], v[120:121], v[122:123] op_sel_hi:[1,0]
	v_pk_mul_f32 v[116:117], v[116:117], v[122:123] op_sel_hi:[1,0]
	v_mul_f32_e32 v119, v119, v119
	v_mul_f32_e32 v115, v115, v115
	v_fmac_f32_e32 v119, v118, v118
	v_mul_f32_e32 v118, v121, v121
	v_fmac_f32_e32 v115, v114, v114
	v_mul_f32_e32 v114, v117, v117
	v_fmac_f32_e32 v118, v120, v120
	v_fmac_f32_e32 v114, v116, v116
	v_add_f32_e32 v118, v119, v118
	v_add_f32_e32 v114, v115, v114
	v_add_f32_e32 v114, v118, v114
	ds_bpermute_b32 v115, v155, v114
	v_cndmask_b32_e32 v153, v201, v207, vcc
	v_lshlrev_b32_e32 v153, 2, v153
	s_waitcnt lgkmcnt(0)
; #define RS ((float*)(WSP() + WS_RS))
;     __device__ __forceinline__ void operator()(const f32x4 (&acc)[2][2][4][2], const Unit& u, int wr, int wc, int fr, int fq) const {
;     ...
;                 for (int bj = 0; bj < 2; ++bj) { float mx = 0.f;
; #pragma unroll
;                     for (int m = 0; m < 4; ++m) { const float rs = RS[row0 + ai * HALF + m * 16] * sc; const f32x4 v0 = acc[ai][bj][m][0] * rs, v1 = acc[ai][bj][m][1] * rs;
;                         float ss = ((v0[0] * v0[0] + v0[1] * v0[1]) + (v0[2] * v0[2] + v0[3] * v0[3])) + ((v1[0] * v1[0] + v1[1] * v1[1]) + (v1[2] * v1[2] + v1[3] * v1[3]));
;                         ss += __shfl_xor(ss, 16); ss += __shfl_xor(ss, 32); mx = fmaxf(mx, ss); }
;                     mx = fmaxf(mx, __shfl_xor(mx, 1)); mx = fmaxf(mx, __shfl_xor(mx, 2)); mx = fmaxf(mx, __shfl_xor(mx, 4)); mx = fmaxf(mx, __shfl_xor(mx, 8));
;                     if (fr == 0 && fq == 0) NRM[(((u.pn - qtile) * 2 + (wc & 1)) * 512 + (u.pm * 4 + ai * 2 + wr)) * 4 + bj * 2 + (wc >> 1)] = mx; } } }
	v_add_f32_e32 v114, v114, v115
	ds_bpermute_b32 v115, v154, v114
	s_waitcnt lgkmcnt(0)
	v_add_f32_e32 v114, v114, v115
	v_max3_f32 v115, v123, 0, v114
	s_nop 1
	v_mov_b32_e32 v114, v236
	v_mul_f32_e32 v114, v140, v114
	v_pk_mul_f32 v[110:111], v[110:111], v[114:115] op_sel_hi:[1,0]
	v_pk_mul_f32 v[106:107], v[106:107], v[114:115] op_sel_hi:[1,0]
	v_pk_mul_f32 v[112:113], v[112:113], v[114:115] op_sel_hi:[1,0]
	v_pk_mul_f32 v[108:109], v[108:109], v[114:115] op_sel_hi:[1,0]
	v_mul_f32_e32 v111, v111, v111
	v_mul_f32_e32 v107, v107, v107
	v_fmac_f32_e32 v111, v110, v110
	v_mul_f32_e32 v110, v113, v113
	v_fmac_f32_e32 v107, v106, v106
	v_mul_f32_e32 v106, v109, v109
	v_fmac_f32_e32 v110, v112, v112
	v_fmac_f32_e32 v106, v108, v108
	v_add_f32_e32 v110, v111, v110
	v_add_f32_e32 v106, v107, v106
	v_add_f32_e32 v106, v110, v106
	ds_bpermute_b32 v107, v155, v106
	s_waitcnt lgkmcnt(0)
	v_add_f32_e32 v106, v106, v107
	ds_bpermute_b32 v107, v154, v106
	s_waitcnt lgkmcnt(0)
	v_add_f32_e32 v107, v106, v107
	s_nop 1
	v_mov_b32_e32 v106, v237
	v_mul_f32_e32 v106, v140, v106
	v_pk_mul_f32 v[102:103], v[102:103], v[106:107] op_sel_hi:[1,0]
	v_pk_mul_f32 v[98:99], v[98:99], v[106:107] op_sel_hi:[1,0]
	v_pk_mul_f32 v[104:105], v[104:105], v[106:107] op_sel_hi:[1,0]
	v_pk_mul_f32 v[100:101], v[100:101], v[106:107] op_sel_hi:[1,0]
	v_mul_f32_e32 v103, v103, v103
	v_mul_f32_e32 v99, v99, v99
	v_fmac_f32_e32 v103, v102, v102
	v_mul_f32_e32 v102, v105, v105
	v_fmac_f32_e32 v99, v98, v98
	v_mul_f32_e32 v98, v101, v101
	v_fmac_f32_e32 v102, v104, v104
	v_fmac_f32_e32 v98, v100, v100
	v_add_f32_e32 v102, v103, v102
	v_add_f32_e32 v98, v99, v98
	v_add_f32_e32 v98, v102, v98
	ds_bpermute_b32 v99, v155, v98
	s_waitcnt lgkmcnt(0)
	v_add_f32_e32 v98, v98, v99
	ds_bpermute_b32 v99, v154, v98
	s_waitcnt lgkmcnt(0)
	v_add_f32_e32 v98, v98, v99
	v_max3_f32 v98, v115, v107, v98
	ds_bpermute_b32 v99, v150, v98
	s_waitcnt lgkmcnt(0)
	v_max_f32_e32 v99, v99, v99
	v_max_f32_e32 v98, v98, v99
	ds_bpermute_b32 v99, v151, v98
	s_waitcnt lgkmcnt(0)
	v_max_f32_e32 v99, v99, v99
	v_max_f32_e32 v98, v98, v99
	ds_bpermute_b32 v99, v152, v98
	s_waitcnt lgkmcnt(0)
	v_max_f32_e32 v99, v99, v99
	v_max_f32_e32 v98, v98, v99
	ds_bpermute_b32 v99, v153, v98
	s_and_saveexec_b64 s[26:27], s[4:5]
	s_cbranch_execz .LBB0_192
	s_ashr_i32 s25, s24, 31
	s_lshl_b64 s[28:29], s[24:25], 2
	s_add_u32 s28, s73, s28
	s_waitcnt lgkmcnt(0)
	v_max_f32_e32 v99, v99, v99
	v_max_f32_e32 v98, v98, v98
	s_addc_u32 s29, s74, s29
	v_max_f32_e32 v98, v98, v99
	global_store_dword v1, v98, s[28:29]
	s_nop 1
	v_mov_b32_e32 v98, v236
	v_mul_f32_e32 v114, v140, v98
.LBB0_192:
	s_or_b64 exec, exec, s[26:27]
	s_nop 1
	v_mov_b32_e32 v98, v234
	s_waitcnt lgkmcnt(0)
	s_nop 1
	v_mov_b32_e32 v99, v235
	s_nop 1
	v_mov_b32_e32 v100, v237
	v_pk_mul_f32 v[96:97], v[96:97], v[114:115] op_sel_hi:[1,0]
	v_mov_b32_e32 v115, v114
	v_pk_mul_f32 v[94:95], v[94:95], v[114:115]
	v_pk_mul_f32 v[88:89], v[88:89], v[114:115] op_sel_hi:[1,0]
	v_pk_mul_f32 v[86:87], v[86:87], v[114:115]
	v_mul_f32_e32 v97, v97, v97
	v_mul_f32_e32 v95, v95, v95
	v_mul_f32_e32 v87, v87, v87
	v_mul_f32_e32 v89, v89, v89
	v_fmac_f32_e32 v97, v96, v96
	v_fmac_f32_e32 v95, v94, v94
	v_fmac_f32_e32 v87, v86, v86
	v_fmac_f32_e32 v89, v88, v88
	v_add_f32_e32 v86, v95, v97
	v_add_f32_e32 v87, v87, v89
	v_add_f32_e32 v86, v86, v87
	ds_bpermute_b32 v87, v155, v86
	s_waitcnt lgkmcnt(0)
	v_add_f32_e32 v87, v86, v87
	ds_bpermute_b32 v89, v154, v87
	v_mul_f32_e32 v86, v140, v98
	v_mul_f32_e32 v88, v140, v99
	v_mul_f32_e32 v94, v140, v100
	v_pk_mul_f32 v[92:93], v[92:93], v[86:87] op_sel_hi:[1,0]
	v_pk_mul_f32 v[90:91], v[90:91], v[86:87] op_sel_hi:[1,0]
	v_pk_mul_f32 v[84:85], v[84:85], v[86:87] op_sel_hi:[1,0]
	v_pk_mul_f32 v[82:83], v[82:83], v[86:87] op_sel_hi:[1,0]
	s_waitcnt lgkmcnt(0)
	v_pk_mul_f32 v[80:81], v[80:81], v[88:89] op_sel_hi:[1,0]
	v_pk_mul_f32 v[78:79], v[78:79], v[88:89] op_sel_hi:[1,0]
	v_pk_mul_f32 v[76:77], v[76:77], v[88:89] op_sel_hi:[1,0]
	v_pk_mul_f32 v[74:75], v[74:75], v[88:89] op_sel_hi:[1,0]
	v_pk_mul_f32 v[72:73], v[72:73], v[94:95] op_sel_hi:[1,0]
	v_pk_mul_f32 v[70:71], v[70:71], v[94:95] op_sel_hi:[1,0]
	v_pk_mul_f32 v[68:69], v[68:69], v[94:95] op_sel_hi:[1,0]
	v_pk_mul_f32 v[66:67], v[66:67], v[94:95] op_sel_hi:[1,0]
	v_mul_f32_e32 v86, v91, v91
	v_mul_f32_e32 v88, v93, v93
	v_mul_f32_e32 v83, v83, v83
	v_mul_f32_e32 v85, v85, v85
	v_mul_f32_e32 v79, v79, v79
	v_mul_f32_e32 v81, v81, v81
	v_mul_f32_e32 v75, v75, v75
	v_mul_f32_e32 v77, v77, v77
	v_mul_f32_e32 v71, v71, v71
	v_mul_f32_e32 v73, v73, v73
	v_mul_f32_e32 v67, v67, v67
	v_mul_f32_e32 v69, v69, v69
	v_fmac_f32_e32 v86, v90, v90
	v_fmac_f32_e32 v88, v92, v92
	v_fmac_f32_e32 v83, v82, v82
	v_fmac_f32_e32 v85, v84, v84
	v_fmac_f32_e32 v79, v78, v78
	v_fmac_f32_e32 v81, v80, v80
	v_fmac_f32_e32 v75, v74, v74
	v_fmac_f32_e32 v77, v76, v76
	v_fmac_f32_e32 v71, v70, v70
	v_fmac_f32_e32 v73, v72, v72
	v_fmac_f32_e32 v67, v66, v66
	v_fmac_f32_e32 v69, v68, v68
	v_add_f32_e32 v66, v86, v88
	v_add_f32_e32 v68, v83, v85
	v_add_f32_e32 v70, v79, v81
	v_add_f32_e32 v72, v75, v77
	v_add_f32_e32 v71, v71, v73
	v_add_f32_e32 v66, v66, v68
	v_add_f32_e32 v68, v70, v72
	v_add_f32_e32 v67, v67, v69
	ds_bpermute_b32 v70, v155, v66
	ds_bpermute_b32 v72, v155, v68
	v_add_f32_e32 v67, v71, v67
	ds_bpermute_b32 v69, v155, v67
	s_waitcnt lgkmcnt(2)
	v_add_f32_e32 v66, v66, v70
	s_waitcnt lgkmcnt(1)
	v_add_f32_e32 v68, v68, v72
	ds_bpermute_b32 v70, v154, v66
	ds_bpermute_b32 v71, v154, v68
	s_waitcnt lgkmcnt(2)
	v_add_f32_e32 v67, v67, v69
	ds_bpermute_b32 v69, v154, v67
	v_add_f32_e32 v72, v87, v89
	s_waitcnt lgkmcnt(2)
	v_add_f32_e32 v66, v66, v70
	s_waitcnt lgkmcnt(1)
	v_add_f32_e32 v68, v68, v71
	v_max3_f32 v66, v66, 0, v68
	s_waitcnt lgkmcnt(0)
	v_add_f32_e32 v67, v67, v69
	v_max3_f32 v66, v66, v72, v67
	ds_bpermute_b32 v67, v150, v66
	s_waitcnt lgkmcnt(0)
	v_max_f32_e32 v67, v67, v67
	v_max_f32_e32 v66, v66, v67
	ds_bpermute_b32 v67, v151, v66
	s_waitcnt lgkmcnt(0)
	v_max_f32_e32 v67, v67, v67
	v_max_f32_e32 v66, v66, v67
	ds_bpermute_b32 v67, v152, v66
	s_waitcnt lgkmcnt(0)
	v_max_f32_e32 v67, v67, v67
	v_max_f32_e32 v66, v66, v67
	ds_bpermute_b32 v67, v153, v66
	s_and_saveexec_b64 s[26:27], s[4:5]
	s_cbranch_execz .LBB0_194
	s_ashr_i32 s25, s24, 31
	s_lshl_b64 s[24:25], s[24:25], 2
	s_waitcnt lgkmcnt(0)
	v_max_f32_e32 v67, v67, v67
	v_max_f32_e32 v66, v66, v66
	s_add_u32 s24, s73, s24
	v_max_f32_e32 v66, v66, v67
	s_addc_u32 s25, s74, s25
	global_store_dword v1, v66, s[24:25] offset:8
; #define RS ((float*)(WSP() + WS_RS))
;     __device__ __forceinline__ void operator()(const f32x4 (&acc)[2][2][4][2], const Unit& u, int wr, int wc, int fr, int fq) const {
;     ...
;                 for (int bj = 0; bj < 2; ++bj) { float mx = 0.f;
; #pragma unroll
;                     for (int m = 0; m < 4; ++m) { const float rs = RS[row0 + ai * HALF + m * 16] * sc; const f32x4 v0 = acc[ai][bj][m][0] * rs, v1 = acc[ai][bj][m][1] * rs;
;                         float ss = ((v0[0] * v0[0] + v0[1] * v0[1]) + (v0[2] * v0[2] + v0[3] * v0[3])) + ((v1[0] * v1[0] + v1[1] * v1[1]) + (v1[2] * v1[2] + v1[3] * v1[3]));
;                         ss += __shfl_xor(ss, 16); ss += __shfl_xor(ss, 32); mx = fmaxf(mx, ss); }
;                     mx = fmaxf(mx, __shfl_xor(mx, 1)); mx = fmaxf(mx, __shfl_xor(mx, 2)); mx = fmaxf(mx, __shfl_xor(mx, 4)); mx = fmaxf(mx, __shfl_xor(mx, 8));
;                     if (fr == 0 && fq == 0) NRM[(((u.pn - qtile) * 2 + (wc & 1)) * 512 + (u.pm * 4 + ai * 2 + wr)) * 4 + bj * 2 + (wc >> 1)] = mx; } } }
.LBB0_194:
	s_or_b64 exec, exec, s[26:27]
	s_nop 1
	v_mov_b32_e32 v66, v238
	s_add_i32 s24, s17, s79
	v_mul_f32_e32 v66, v140, v66
	s_waitcnt lgkmcnt(0)
	v_pk_mul_f32 v[62:63], v[62:63], v[66:67] op_sel_hi:[1,0]
	v_pk_mul_f32 v[58:59], v[58:59], v[66:67] op_sel_hi:[1,0]
	v_pk_mul_f32 v[64:65], v[64:65], v[66:67] op_sel_hi:[1,0]
	v_pk_mul_f32 v[60:61], v[60:61], v[66:67] op_sel_hi:[1,0]
	v_mul_f32_e32 v63, v63, v63
	v_mul_f32_e32 v59, v59, v59
	v_fmac_f32_e32 v63, v62, v62
	v_mul_f32_e32 v62, v65, v65
	v_fmac_f32_e32 v59, v58, v58
	v_mul_f32_e32 v58, v61, v61
	v_fmac_f32_e32 v62, v64, v64
	v_fmac_f32_e32 v58, v60, v60
	v_add_f32_e32 v62, v63, v62
	v_add_f32_e32 v58, v59, v58
	v_add_f32_e32 v58, v62, v58
	ds_bpermute_b32 v59, v155, v58
	s_waitcnt lgkmcnt(0)
	v_add_f32_e32 v58, v58, v59
	ds_bpermute_b32 v59, v154, v58
	s_waitcnt lgkmcnt(0)
	v_add_f32_e32 v59, v58, v59
	s_nop 1
	v_mov_b32_e32 v58, v239
	v_mul_f32_e32 v58, v140, v58
	v_pk_mul_f32 v[54:55], v[54:55], v[58:59] op_sel_hi:[1,0]
	v_pk_mul_f32 v[50:51], v[50:51], v[58:59] op_sel_hi:[1,0]
	v_pk_mul_f32 v[56:57], v[56:57], v[58:59] op_sel_hi:[1,0]
	v_pk_mul_f32 v[52:53], v[52:53], v[58:59] op_sel_hi:[1,0]
	v_mul_f32_e32 v55, v55, v55
	v_mul_f32_e32 v51, v51, v51
	v_fmac_f32_e32 v55, v54, v54
	v_mul_f32_e32 v54, v57, v57
	v_fmac_f32_e32 v51, v50, v50
	v_mul_f32_e32 v50, v53, v53
	v_fmac_f32_e32 v54, v56, v56
	v_fmac_f32_e32 v50, v52, v52
	v_add_f32_e32 v54, v55, v54
	v_add_f32_e32 v50, v51, v50
	v_add_f32_e32 v50, v54, v50
	ds_bpermute_b32 v51, v155, v50
	s_waitcnt lgkmcnt(0)
	v_add_f32_e32 v50, v50, v51
	ds_bpermute_b32 v51, v154, v50
	s_waitcnt lgkmcnt(0)
	v_add_f32_e32 v50, v50, v51
	v_max3_f32 v51, v59, 0, v50
	s_nop 1
	v_mov_b32_e32 v50, v240
	v_mul_f32_e32 v50, v140, v50
	v_pk_mul_f32 v[46:47], v[46:47], v[50:51] op_sel_hi:[1,0]
	v_pk_mul_f32 v[42:43], v[42:43], v[50:51] op_sel_hi:[1,0]
	v_pk_mul_f32 v[48:49], v[48:49], v[50:51] op_sel_hi:[1,0]
	v_pk_mul_f32 v[44:45], v[44:45], v[50:51] op_sel_hi:[1,0]
	v_mul_f32_e32 v47, v47, v47
	v_mul_f32_e32 v43, v43, v43
	v_fmac_f32_e32 v47, v46, v46
	v_mul_f32_e32 v46, v49, v49
	v_fmac_f32_e32 v43, v42, v42
	v_mul_f32_e32 v42, v45, v45
	v_fmac_f32_e32 v46, v48, v48
	v_fmac_f32_e32 v42, v44, v44
	v_add_f32_e32 v46, v47, v46
	v_add_f32_e32 v42, v43, v42
	v_add_f32_e32 v42, v46, v42
	ds_bpermute_b32 v43, v155, v42
	s_waitcnt lgkmcnt(0)
	v_add_f32_e32 v42, v42, v43
	ds_bpermute_b32 v43, v154, v42
	s_waitcnt lgkmcnt(0)
	v_add_f32_e32 v43, v42, v43
	s_nop 1
	v_mov_b32_e32 v42, v241
	v_mul_f32_e32 v42, v140, v42
	v_pk_mul_f32 v[38:39], v[38:39], v[42:43] op_sel_hi:[1,0]
	v_pk_mul_f32 v[34:35], v[34:35], v[42:43] op_sel_hi:[1,0]
	v_pk_mul_f32 v[40:41], v[40:41], v[42:43] op_sel_hi:[1,0]
	v_pk_mul_f32 v[36:37], v[36:37], v[42:43] op_sel_hi:[1,0]
	v_mul_f32_e32 v39, v39, v39
	v_mul_f32_e32 v35, v35, v35
	v_fmac_f32_e32 v39, v38, v38
	v_mul_f32_e32 v38, v41, v41
	v_fmac_f32_e32 v35, v34, v34
	v_mul_f32_e32 v34, v37, v37
	v_fmac_f32_e32 v38, v40, v40
	v_fmac_f32_e32 v34, v36, v36
	v_add_f32_e32 v38, v39, v38
	v_add_f32_e32 v34, v35, v34
	v_add_f32_e32 v34, v38, v34
	ds_bpermute_b32 v35, v155, v34
	s_waitcnt lgkmcnt(0)
	v_add_f32_e32 v34, v34, v35
	ds_bpermute_b32 v35, v154, v34
	s_waitcnt lgkmcnt(0)
	v_add_f32_e32 v34, v34, v35
	v_max3_f32 v34, v51, v43, v34
	ds_bpermute_b32 v35, v150, v34
	s_waitcnt lgkmcnt(0)
	v_max_f32_e32 v35, v35, v35
	v_max_f32_e32 v34, v34, v35
	ds_bpermute_b32 v35, v151, v34
	s_waitcnt lgkmcnt(0)
	v_max_f32_e32 v35, v35, v35
	v_max_f32_e32 v34, v34, v35
	ds_bpermute_b32 v35, v152, v34
	s_waitcnt lgkmcnt(0)
	v_max_f32_e32 v35, v35, v35
	v_max_f32_e32 v34, v34, v35
	ds_bpermute_b32 v35, v153, v34
	s_and_saveexec_b64 s[26:27], s[4:5]
	s_cbranch_execz .LBB0_196
	s_ashr_i32 s25, s24, 31
	s_lshl_b64 s[28:29], s[24:25], 2
	s_add_u32 s28, s73, s28
	s_waitcnt lgkmcnt(0)
	v_max_f32_e32 v35, v35, v35
	v_max_f32_e32 v34, v34, v34
	s_addc_u32 s29, s74, s29
	v_max_f32_e32 v34, v34, v35
	global_store_dword v1, v34, s[28:29]
	s_nop 1
	v_mov_b32_e32 v34, v240
	v_mul_f32_e32 v50, v140, v34
; #define RS ((float*)(WSP() + WS_RS))
;     __device__ __forceinline__ void operator()(const f32x4 (&acc)[2][2][4][2], const Unit& u, int wr, int wc, int fr, int fq) const {
;     ...
;                 for (int bj = 0; bj < 2; ++bj) { float mx = 0.f;
; #pragma unroll
;                     for (int m = 0; m < 4; ++m) { const float rs = RS[row0 + ai * HALF + m * 16] * sc; const f32x4 v0 = acc[ai][bj][m][0] * rs, v1 = acc[ai][bj][m][1] * rs;
;                         float ss = ((v0[0] * v0[0] + v0[1] * v0[1]) + (v0[2] * v0[2] + v0[3] * v0[3])) + ((v1[0] * v1[0] + v1[1] * v1[1]) + (v1[2] * v1[2] + v1[3] * v1[3]));
;                         ss += __shfl_xor(ss, 16); ss += __shfl_xor(ss, 32); mx = fmaxf(mx, ss); }
;                     mx = fmaxf(mx, __shfl_xor(mx, 1)); mx = fmaxf(mx, __shfl_xor(mx, 2)); mx = fmaxf(mx, __shfl_xor(mx, 4)); mx = fmaxf(mx, __shfl_xor(mx, 8));
;                     if (fr == 0 && fq == 0) NRM[(((u.pn - qtile) * 2 + (wc & 1)) * 512 + (u.pm * 4 + ai * 2 + wr)) * 4 + bj * 2 + (wc >> 1)] = mx; } } }
.LBB0_196:
	s_or_b64 exec, exec, s[26:27]
	s_nop 1
	v_mov_b32_e32 v34, v238
	s_waitcnt lgkmcnt(0)
	s_nop 1
	v_mov_b32_e32 v35, v239
	s_nop 1
	v_mov_b32_e32 v36, v241
	v_pk_mul_f32 v[32:33], v[32:33], v[50:51] op_sel_hi:[1,0]
	v_mov_b32_e32 v51, v50
	v_pk_mul_f32 v[30:31], v[30:31], v[50:51]
	v_pk_mul_f32 v[24:25], v[24:25], v[50:51] op_sel_hi:[1,0]
	v_pk_mul_f32 v[22:23], v[22:23], v[50:51]
	v_mul_f32_e32 v33, v33, v33
	v_mul_f32_e32 v31, v31, v31
	v_mul_f32_e32 v23, v23, v23
	v_mul_f32_e32 v25, v25, v25
	v_fmac_f32_e32 v33, v32, v32
	v_fmac_f32_e32 v31, v30, v30
	v_fmac_f32_e32 v23, v22, v22
	v_fmac_f32_e32 v25, v24, v24
	v_add_f32_e32 v22, v31, v33
	v_add_f32_e32 v23, v23, v25
	v_add_f32_e32 v22, v22, v23
	ds_bpermute_b32 v23, v155, v22
	s_waitcnt lgkmcnt(0)
	v_add_f32_e32 v23, v22, v23
	ds_bpermute_b32 v25, v154, v23
	v_mul_f32_e32 v22, v140, v34
	v_mul_f32_e32 v24, v140, v35
	v_mul_f32_e32 v30, v140, v36
	v_pk_mul_f32 v[28:29], v[28:29], v[22:23] op_sel_hi:[1,0]
	v_pk_mul_f32 v[26:27], v[26:27], v[22:23] op_sel_hi:[1,0]
	v_pk_mul_f32 v[20:21], v[20:21], v[22:23] op_sel_hi:[1,0]
	v_pk_mul_f32 v[18:19], v[18:19], v[22:23] op_sel_hi:[1,0]
	s_waitcnt lgkmcnt(0)
	v_pk_mul_f32 v[16:17], v[16:17], v[24:25] op_sel_hi:[1,0]
	v_pk_mul_f32 v[14:15], v[14:15], v[24:25] op_sel_hi:[1,0]
	v_pk_mul_f32 v[12:13], v[12:13], v[24:25] op_sel_hi:[1,0]
	v_pk_mul_f32 v[10:11], v[10:11], v[24:25] op_sel_hi:[1,0]
	v_pk_mul_f32 v[8:9], v[8:9], v[30:31] op_sel_hi:[1,0]
	v_pk_mul_f32 v[6:7], v[6:7], v[30:31] op_sel_hi:[1,0]
	v_pk_mul_f32 v[4:5], v[4:5], v[30:31] op_sel_hi:[1,0]
	v_pk_mul_f32 v[2:3], v[2:3], v[30:31] op_sel_hi:[1,0]
	v_mul_f32_e32 v22, v27, v27
	v_mul_f32_e32 v24, v29, v29
	v_mul_f32_e32 v19, v19, v19
	v_mul_f32_e32 v21, v21, v21
	v_mul_f32_e32 v15, v15, v15
	v_mul_f32_e32 v17, v17, v17
	v_mul_f32_e32 v11, v11, v11
	v_mul_f32_e32 v13, v13, v13
	v_mul_f32_e32 v7, v7, v7
	v_mul_f32_e32 v9, v9, v9
	v_mul_f32_e32 v3, v3, v3
	v_mul_f32_e32 v5, v5, v5
	v_fmac_f32_e32 v22, v26, v26
	v_fmac_f32_e32 v24, v28, v28
	v_fmac_f32_e32 v19, v18, v18
	v_fmac_f32_e32 v21, v20, v20
	v_fmac_f32_e32 v15, v14, v14
	v_fmac_f32_e32 v17, v16, v16
	v_fmac_f32_e32 v11, v10, v10
	v_fmac_f32_e32 v13, v12, v12
	v_fmac_f32_e32 v7, v6, v6
	v_fmac_f32_e32 v9, v8, v8
	v_fmac_f32_e32 v3, v2, v2
	v_fmac_f32_e32 v5, v4, v4
	v_add_f32_e32 v2, v22, v24
	v_add_f32_e32 v4, v19, v21
	v_add_f32_e32 v6, v15, v17
	v_add_f32_e32 v8, v11, v13
	v_add_f32_e32 v7, v7, v9
	v_add_f32_e32 v2, v2, v4
	v_add_f32_e32 v4, v6, v8
	v_add_f32_e32 v3, v3, v5
	ds_bpermute_b32 v6, v155, v2
	ds_bpermute_b32 v8, v155, v4
	v_add_f32_e32 v3, v7, v3
	ds_bpermute_b32 v5, v155, v3
	s_waitcnt lgkmcnt(2)
	v_add_f32_e32 v2, v2, v6
	s_waitcnt lgkmcnt(1)
	v_add_f32_e32 v4, v4, v8
	ds_bpermute_b32 v6, v154, v2
	ds_bpermute_b32 v7, v154, v4
	s_waitcnt lgkmcnt(2)
	v_add_f32_e32 v3, v3, v5
	ds_bpermute_b32 v5, v154, v3
	v_add_f32_e32 v8, v23, v25
	s_waitcnt lgkmcnt(2)
	v_add_f32_e32 v2, v2, v6
	s_waitcnt lgkmcnt(1)
	v_add_f32_e32 v4, v4, v7
	v_max3_f32 v2, v2, 0, v4
	s_waitcnt lgkmcnt(0)
	v_add_f32_e32 v3, v3, v5
	v_max3_f32 v2, v2, v8, v3
	ds_bpermute_b32 v3, v150, v2
	s_waitcnt lgkmcnt(0)
	v_max_f32_e32 v3, v3, v3
	v_max_f32_e32 v2, v2, v3
	ds_bpermute_b32 v3, v151, v2
	s_waitcnt lgkmcnt(0)
	v_max_f32_e32 v3, v3, v3
	v_max_f32_e32 v2, v2, v3
	ds_bpermute_b32 v3, v152, v2
	s_waitcnt lgkmcnt(0)
	v_max_f32_e32 v3, v3, v3
	v_max_f32_e32 v2, v2, v3
	ds_bpermute_b32 v3, v153, v2
	s_and_saveexec_b64 s[26:27], s[4:5]
	s_cbranch_execz .LBB0_198
	s_ashr_i32 s25, s24, 31
	s_lshl_b64 s[24:25], s[24:25], 2
	s_waitcnt lgkmcnt(0)
	v_max_f32_e32 v3, v3, v3
	v_max_f32_e32 v2, v2, v2
	s_add_u32 s24, s73, s24
	v_max_f32_e32 v2, v2, v3
	s_addc_u32 s25, s74, s25
	global_store_dword v1, v2, s[24:25] offset:8
